# global barriers: the 20th-of-32 arriver of each XCD also issues buffer_wbl2 (early partial L2 flush off the critical path)
# speedup vs baseline: 1.0030x; 1.0030x over previous
; __device__ __forceinline__ unsigned xb_ld(unsigned* p)              { return __hip_atomic_load(p, __ATOMIC_RELAXED, __HIP_MEMORY_SCOPE_AGENT); }
; __device__ __forceinline__ unsigned xb_add(unsigned* p, unsigned v) { return __hip_atomic_fetch_add(p, v, __ATOMIC_RELAXED, __HIP_MEMORY_SCOPE_AGENT); }
; #define XB_SPIN(cond, bar) do { unsigned _sp = 0; while (cond) { __builtin_amdgcn_s_sleep(1); \
;     if ((++_sp & 255u) == 0u) { if (xb_ld(&(bar)[XB_TMO])) break; if (_sp > XB_SPIN_CAP) { atomicAdd(&(bar)[XB_TMO], 1u); break; } } } } while (0)
; __device__ __forceinline__ void xcd_barrier(const XcdBarrier& b) {
;     ...
;     if (threadIdx.x == 0) {
;         unsigned* bar = b.bar;
;         __builtin_amdgcn_s_waitcnt(0);
;         unsigned nloc = b.st[0], nx = b.st[1];
;         if (nloc == 0u) { xcd_barrier_complete(bar, b.x, nloc, nx); b.st[0] = nloc; b.st[1] = nx; }
;         const unsigned old = xb_add(&bar[XB_XSUB(b.x)], 1u);
;         const unsigned gen = old / nloc;
;         if (old + 1u == (gen + 1u) * nloc) {
;             __builtin_amdgcn_fence(__ATOMIC_RELEASE, "agent");
;             asm volatile("s_waitcnt vmcnt(0)" ::: "memory");
;             const unsigned og = xb_add(&bar[XB_TOP], 1u);
;             const unsigned tg = og / nx;
;             if (og + 1u == (tg + 1u) * nx) xb_add(&bar[XB_TOPGEN], 1u);
;             else XB_SPIN(xb_ld(&bar[XB_TOPGEN]) == tg, bar);
;             __builtin_amdgcn_fence(__ATOMIC_ACQUIRE, "agent");
;             xb_add(&bar[XB_XGEN(b.x)], 1u);
;             asm volatile("s_waitcnt vmcnt(0)" ::: "memory");
.LBB0_120:
	s_lshl_b32 s6, s3, 8
	s_add_u32 s6, s20, s6
	s_addc_u32 s7, s21, 0
	s_mov_b32 s100, 1
	s_mov_b32 s101, 0
	s_and_b32 s98, s2, 7
	s_lshl_b32 s10, s98, 2
	s_add_u32 s8, s58, s10
	s_addc_u32 s9, s59, 0
	s_add_u32 s8, s8, 0x900100
	s_addc_u32 s9, s9, 0
	s_lshl_b32 s10, 1, s3
	v_mov_b32_e32 v3, s10
	v_mov_b32_e32 v4, 0
	global_atomic_or v4, v3, s[8:9]
	s_lshl_b32 s98, s98, 8
	s_add_i32 s98, s98, 0x902400
	v_mov_b32_e32 v3, 1
	v_mov_b32_e32 v4, 0x1000
	global_atomic_add v3, v4, v3, s[6:7] offset:1024 sc0
	s_add_u32 s8, s58, 0x903400
	s_addc_u32 s9, s59, 0
	v_mov_b32_e32 v4, 0
	s_waitcnt lgkmcnt(0)
	v_mul_u32_u24_e32 v5, s100, v2
	v_mul_u32_u24_e32 v6, s100, v0
	s_waitcnt vmcnt(0)
	v_add_u32_e32 v3, 1, v3
	v_cmp_ne_u32_e32 vcc, v3, v5
	s_cbranch_vccnz .Lgbar_mid_0
	buffer_wbl2 sc1
	s_waitcnt vmcnt(0)
	v_mov_b32_e32 v3, 1
	global_atomic_add v4, v3, s[8:9]
	s_branch .Lgbar_poll_0
.Lgbar_mid_0:
	v_add_u32_e32 v3, 12, v3
	v_cmp_ne_u32_e32 vcc, v3, v5
	s_cbranch_vccnz .Lgbar_poll_0
	buffer_wbl2 sc1
	s_waitcnt vmcnt(0)

; __device__ __forceinline__ unsigned xb_ld(unsigned* p)              { return __hip_atomic_load(p, __ATOMIC_RELAXED, __HIP_MEMORY_SCOPE_AGENT); }
; __device__ __forceinline__ unsigned xb_add(unsigned* p, unsigned v) { return __hip_atomic_fetch_add(p, v, __ATOMIC_RELAXED, __HIP_MEMORY_SCOPE_AGENT); }
; #define XB_SPIN(cond, bar) do { unsigned _sp = 0; while (cond) { __builtin_amdgcn_s_sleep(1); \
;     if ((++_sp & 255u) == 0u) { if (xb_ld(&(bar)[XB_TMO])) break; if (_sp > XB_SPIN_CAP) { atomicAdd(&(bar)[XB_TMO], 1u); break; } } } } while (0)
; __device__ __forceinline__ void xcd_barrier(const XcdBarrier& b) {
;     ...
;     if (threadIdx.x == 0) {
;         unsigned* bar = b.bar;
;         __builtin_amdgcn_s_waitcnt(0);
;         unsigned nloc = b.st[0], nx = b.st[1];
;         if (nloc == 0u) { xcd_barrier_complete(bar, b.x, nloc, nx); b.st[0] = nloc; b.st[1] = nx; }
;         const unsigned old = xb_add(&bar[XB_XSUB(b.x)], 1u);
;         const unsigned gen = old / nloc;
;         if (old + 1u == (gen + 1u) * nloc) {
;             __builtin_amdgcn_fence(__ATOMIC_RELEASE, "agent");
;             asm volatile("s_waitcnt vmcnt(0)" ::: "memory");
;             const unsigned og = xb_add(&bar[XB_TOP], 1u);
;             const unsigned tg = og / nx;
;             if (og + 1u == (tg + 1u) * nx) xb_add(&bar[XB_TOPGEN], 1u);
;             else XB_SPIN(xb_ld(&bar[XB_TOPGEN]) == tg, bar);
;             __builtin_amdgcn_fence(__ATOMIC_ACQUIRE, "agent");
;             xb_add(&bar[XB_XGEN(b.x)], 1u);
;             asm volatile("s_waitcnt vmcnt(0)" ::: "memory");
.LBB0_318:
	s_add_i32 s100, s100, 1
	v_readlane_b32 s4, v240, 0
	v_readlane_b32 s5, v240, 1
	v_mov_b32_e32 v3, 1
	v_mov_b32_e32 v4, 0
	s_nop 4
	global_atomic_add v3, v4, v3, s[4:5] sc0
	v_readlane_b32 s4, v240, 4
	v_readlane_b32 s5, v240, 5
	s_waitcnt lgkmcnt(0)
	v_mul_u32_u24_e32 v5, s100, v2
	v_mul_u32_u24_e32 v6, s100, v0
	s_waitcnt vmcnt(0)
	v_add_u32_e32 v3, 1, v3
	v_cmp_ne_u32_e32 vcc, v3, v5
	s_cbranch_vccnz .Lgbar_mid_3
	buffer_wbl2 sc1
	s_waitcnt vmcnt(0)
	v_mov_b32_e32 v3, 1
	global_atomic_add v4, v3, s[4:5]
	s_branch .Lgbar_poll_3
